# attention tiles: rescale-threshold test on per-lane partial max (cross-half max only on slow/first paths), running row-sum kept per lane-half and combined once at loop exit, dropped add-with-zero; on
# speedup vs baseline: 1.0068x; 1.0023x over previous
.LBB0_134:
	v_add_u32_e32 v80, s0, v120
	v_add_u32_e32 v82, v80, v124
	ds_read_b128 v[138:141], v82 offset:0
	ds_read_b128 v[146:149], v82 offset:0x1000
	s_waitcnt lgkmcnt(2)
	v_add_u32_e32 v118, v80, v125
	v_add_u32_e32 v142, v80, v126
	v_mfma_f32_32x32x16_bf16 v[80:95], v[130:133], v[96:99], v[160:175]
	ds_read_b128 v[130:133], v118 offset:0
	v_mfma_f32_32x32x16_bf16 v[64:79], v[134:137], v[96:99], v[160:175]
	ds_read_b128 v[134:137], v118 offset:0x1000
	s_waitcnt lgkmcnt(2)
	v_mfma_f32_32x32x16_bf16 v[80:95], v[138:141], v[100:103], v[80:95]
	ds_read_b128 v[138:141], v142 offset:0
	v_mfma_f32_32x32x16_bf16 v[64:79], v[146:149], v[100:103], v[64:79]
	ds_read_b128 v[146:149], v142 offset:0x1000
	s_waitcnt lgkmcnt(2)
	v_mfma_f32_32x32x16_bf16 v[80:95], v[130:133], v[104:107], v[80:95]
	s_waitcnt lgkmcnt(0)
	v_mfma_f32_32x32x16_bf16 v[64:79], v[134:137], v[104:107], v[64:79]
	v_mfma_f32_32x32x16_bf16 v[80:95], v[138:141], v[108:111], v[80:95]
	s_cmp_eq_u32 s53, 0
	s_cselect_b64 s[70:71], -1, 0
	s_cmp_lg_u32 s53, 0
	v_mfma_f32_32x32x16_bf16 v[64:79], v[146:149], v[108:111], v[64:79]
	s_nop 7
	v_max_f32_e32 v118, v80, v81
	v_max3_f32 v118, v118, v82, v83
	v_max3_f32 v118, v118, v84, v85
	v_max3_f32 v118, v118, v86, v87
	v_max3_f32 v118, v118, v88, v89
	v_max3_f32 v118, v118, v90, v91
	v_max3_f32 v118, v118, v92, v93
	v_max3_f32 v118, v118, v94, v95
	v_max3_f32 v118, v118, v64, v65
	v_max3_f32 v118, v118, v66, v67
	v_max3_f32 v118, v118, v68, v69
	v_max3_f32 v118, v118, v70, v71
	v_max3_f32 v118, v118, v72, v73
	v_max3_f32 v118, v118, v74, v75
	v_max3_f32 v118, v118, v76, v77
	v_max3_f32 v118, v118, v78, v79
	s_cbranch_scc0 .Lmx1_first
	v_cmp_ge_f32_e32 vcc, s62, v118
	s_cmp_lg_u64 vcc, exec
	s_mov_b64 s[74:75], 0
	s_mov_b64 s[72:73], 0
	s_cbranch_scc1 .Lmx1_slow
	v_mov_b32_e32 v130, 1.0
	s_branch .LBB0_146
.Lmx1_first:
	v_mov_b32_e32 v130, v118
	s_nop 1
	v_permlane32_swap_b32_e32 v118, v130
	v_max_f32_e32 v130, v118, v130
	s_branch .LBB0_139

.LBB0_146:
	v_exp_f32_e32 v80, v80
	v_exp_f32_e32 v81, v81
	v_exp_f32_e32 v82, v82
	v_exp_f32_e32 v83, v83
	v_exp_f32_e32 v84, v84
	v_exp_f32_e32 v118, v64
	v_exp_f32_e32 v85, v85
	v_add_f32_e32 v64, v81, v80
	v_exp_f32_e32 v86, v86
	v_add_f32_e32 v64, v82, v64
	v_exp_f32_e32 v87, v87
	v_add_f32_e32 v64, v83, v64
	v_exp_f32_e32 v88, v88
	v_add_f32_e32 v64, v84, v64
	v_exp_f32_e32 v89, v89
	v_add_f32_e32 v64, v85, v64
	v_exp_f32_e32 v90, v90
	v_add_f32_e32 v64, v86, v64
	v_exp_f32_e32 v91, v91
	v_add_f32_e32 v64, v87, v64
	v_exp_f32_e32 v92, v92
	v_add_f32_e32 v64, v88, v64
	v_exp_f32_e32 v93, v93
	v_add_f32_e32 v64, v89, v64
	v_exp_f32_e32 v94, v94
	v_add_f32_e32 v64, v90, v64
	v_exp_f32_e32 v95, v95
	v_add_f32_e32 v64, v91, v64
	v_add_f32_e32 v64, v92, v64
	v_exp_f32_e32 v65, v65
	v_add_f32_e32 v64, v93, v64
	v_exp_f32_e32 v131, v66
	v_add_f32_e32 v64, v94, v64
	v_exp_f32_e32 v132, v67
	v_add_f32_e32 v64, v95, v64
	v_exp_f32_e32 v133, v68
	v_add_f32_e32 v64, v118, v64
	v_exp_f32_e32 v134, v69
	v_add_f32_e32 v64, v65, v64
	v_exp_f32_e32 v135, v70
	v_add_f32_e32 v64, v131, v64
	v_exp_f32_e32 v136, v71
	v_add_f32_e32 v64, v132, v64
	v_exp_f32_e32 v137, v72
	v_add_f32_e32 v64, v133, v64
	v_exp_f32_e32 v138, v73
	v_add_f32_e32 v64, v134, v64
	v_exp_f32_e32 v139, v74
	v_add_f32_e32 v64, v135, v64
	v_exp_f32_e32 v140, v75
	v_add_f32_e32 v64, v136, v64
	v_exp_f32_e32 v141, v76
	v_add_f32_e32 v64, v137, v64
	v_exp_f32_e32 v142, v77
	v_add_f32_e32 v64, v138, v64
	v_exp_f32_e32 v143, v78
	v_add_f32_e32 v64, v139, v64
	v_exp_f32_e32 v146, v79
	v_add_f32_e32 v64, v140, v64
	v_add_f32_e32 v64, v141, v64
	v_add_f32_e32 v64, v142, v64
	v_add_f32_e32 v64, v143, v64
	v_add_f32_e32 v64, v146, v64
	s_add_i32 s53, s53, 1
	v_fma_f32 v129, v129, v130, v64
	v_cvt_pk_bf16_f32 v66, v80, v81
	v_cvt_pk_bf16_f32 v67, v82, v83
	v_cvt_pk_bf16_f32 v68, v84, v85
	v_cvt_pk_bf16_f32 v69, v86, v87
	v_cvt_pk_bf16_f32 v70, v88, v89
	v_cvt_pk_bf16_f32 v71, v90, v91
	v_cvt_pk_bf16_f32 v72, v92, v93
	v_cvt_pk_bf16_f32 v73, v94, v95
	v_cvt_pk_bf16_f32 v74, v118, v65
	v_cvt_pk_bf16_f32 v75, v131, v132
	v_cvt_pk_bf16_f32 v76, v133, v134
	v_cvt_pk_bf16_f32 v77, v135, v136
	v_cvt_pk_bf16_f32 v78, v137, v138
	v_cvt_pk_bf16_f32 v79, v139, v140
	v_cvt_pk_bf16_f32 v80, v141, v142
	v_cvt_pk_bf16_f32 v81, v143, v146
	s_nop 0
	v_permlane32_swap_b32_e32 v66, v68
	v_permlane32_swap_b32_e32 v67, v69
	v_permlane32_swap_b32_e32 v70, v72
	v_permlane32_swap_b32_e32 v71, v73
	v_permlane32_swap_b32_e32 v74, v76
	v_permlane32_swap_b32_e32 v75, v77
	v_permlane32_swap_b32_e32 v78, v80
	v_permlane32_swap_b32_e32 v79, v81
	v_lshl_add_u32 v65, s80, 14, v127
	ds_read_b64_tr_b16 v[82:83], v65 offset:0
	ds_read_b64_tr_b16 v[84:85], v65 offset:0x800
	ds_read_b64_tr_b16 v[86:87], v65 offset:0x1000
	ds_read_b64_tr_b16 v[88:89], v65 offset:0x1800
	ds_read_b64_tr_b16 v[90:91], v65 offset:0x2000
	ds_read_b64_tr_b16 v[92:93], v65 offset:0x2800
	ds_read_b64_tr_b16 v[130:131], v65 offset:0x3000
	ds_read_b64_tr_b16 v[132:133], v65 offset:0x3800
	ds_read_b64_tr_b16 v[134:135], v65 offset:0x200
	ds_read_b64_tr_b16 v[136:137], v65 offset:0xa00
	ds_read_b64_tr_b16 v[138:139], v65 offset:0x1200
	ds_read_b64_tr_b16 v[140:141], v65 offset:0x1a00
	ds_read_b64_tr_b16 v[146:147], v65 offset:0x2200
	ds_read_b64_tr_b16 v[148:149], v65 offset:0x2a00
	ds_read_b64_tr_b16 v[150:151], v65 offset:0x3200
	ds_read_b64_tr_b16 v[152:153], v65 offset:0x3a00
	s_waitcnt lgkmcnt(8)
	s_nop 0
	v_mfma_f32_32x32x16_bf16 v[48:63], v[66:69], v[82:85], v[48:63]
	ds_read_b64_tr_b16 v[82:83], v65 offset:0x400
	ds_read_b64_tr_b16 v[84:85], v65 offset:0xc00
	v_mfma_f32_32x32x16_bf16 v[48:63], v[70:73], v[86:89], v[48:63]
	ds_read_b64_tr_b16 v[86:87], v65 offset:0x1400
	ds_read_b64_tr_b16 v[88:89], v65 offset:0x1c00
	v_mfma_f32_32x32x16_bf16 v[48:63], v[74:77], v[90:93], v[48:63]
	ds_read_b64_tr_b16 v[90:91], v65 offset:0x2400
	ds_read_b64_tr_b16 v[92:93], v65 offset:0x2c00
	v_mfma_f32_32x32x16_bf16 v[48:63], v[78:81], v[130:133], v[48:63]
	ds_read_b64_tr_b16 v[130:131], v65 offset:0x3400
	ds_read_b64_tr_b16 v[132:133], v65 offset:0x3c00
	s_waitcnt lgkmcnt(8)
	v_mfma_f32_32x32x16_bf16 v[32:47], v[66:69], v[134:137], v[32:47]
	ds_read_b64_tr_b16 v[134:135], v65 offset:0x600
	ds_read_b64_tr_b16 v[136:137], v65 offset:0xe00
	v_mfma_f32_32x32x16_bf16 v[32:47], v[70:73], v[138:141], v[32:47]
	ds_read_b64_tr_b16 v[138:139], v65 offset:0x1600
	ds_read_b64_tr_b16 v[140:141], v65 offset:0x1e00
	v_mfma_f32_32x32x16_bf16 v[32:47], v[74:77], v[146:149], v[32:47]
	ds_read_b64_tr_b16 v[146:147], v65 offset:0x2600
	ds_read_b64_tr_b16 v[148:149], v65 offset:0x2e00
	v_mfma_f32_32x32x16_bf16 v[32:47], v[78:81], v[150:153], v[32:47]
	ds_read_b64_tr_b16 v[150:151], v65 offset:0x3600
	ds_read_b64_tr_b16 v[152:153], v65 offset:0x3e00
	s_waitcnt lgkmcnt(8)
	v_mfma_f32_32x32x16_bf16 v[16:31], v[66:69], v[82:85], v[16:31]
	s_waitcnt lgkmcnt(0)
	v_mfma_f32_32x32x16_bf16 v[16:31], v[70:73], v[86:89], v[16:31]
	v_mfma_f32_32x32x16_bf16 v[16:31], v[74:77], v[90:93], v[16:31]
	v_mfma_f32_32x32x16_bf16 v[16:31], v[78:81], v[130:133], v[16:31]
	v_mfma_f32_32x32x16_bf16 v[0:15], v[66:69], v[134:137], v[0:15]
	s_waitcnt vmcnt(0)
	s_add_i32 s54, s54, 0x8000
	s_cmp_eq_u32 s53, 32
	s_waitcnt vmcnt(0) lgkmcnt(0)
	s_barrier
	s_and_b32 s1, s53, 1
	s_lshl_b32 s1, s1, 13
	v_add3_u32 v118, v120, v123, s1
	ds_read_b128 v[130:133], v118 offset:0
	ds_read_b128 v[134:137], v118 offset:0x1000
	s_cmp_eq_u32 s53, 32
	v_mfma_f32_32x32x16_bf16 v[0:15], v[70:73], v[138:141], v[0:15]
	v_mfma_f32_32x32x16_bf16 v[0:15], v[74:77], v[146:149], v[0:15]
	v_mfma_f32_32x32x16_bf16 v[0:15], v[78:81], v[150:153], v[0:15]
	s_cbranch_scc1 .LBB0_148
	s_and_b32 s80, s53, 1
	s_cmp_eq_u32 s53, 31
	s_movk_i32 s0, 0x2000
	s_cbranch_scc0 .LBB0_133
	s_branch .LBB0_134
.LBB0_148:
	v_mov_b32_e32 v66, v129
	s_nop 1
	v_permlane32_swap_b32_e32 v129, v66
	v_add_f32_e32 v64, v129, v66
	s_and_saveexec_b64 s[0:1], s[6:7]
	ds_write_b32 v122, v64
	s_or_b64 exec, exec, s[0:1]
	v_lshlrev_b32_e32 v64, 6, v121
	v_ashrrev_i32_e32 v65, 31, v64
	s_waitcnt lgkmcnt(0)
	v_add_u32_e32 v80, v119, v184
	v_lshl_add_u64 v[112:113], v[64:65], 2, s[12:13]
	ds_read_b128 v[64:67], v80
	ds_read_b128 v[68:71], v80 offset:32
	s_mov_b32 s5, 0
	v_mov_b32_e32 v130, 0
	v_mov_b32_e32 v131, 0
	s_waitcnt lgkmcnt(1)
	v_rcp_f32_e32 v72, v64
	v_rcp_f32_e32 v73, v65
	v_rcp_f32_e32 v74, v66
	v_rcp_f32_e32 v75, v67
	ds_read_b128 v[64:67], v80 offset:64
	s_waitcnt lgkmcnt(1)
	v_rcp_f32_e32 v68, v68
	v_rcp_f32_e32 v69, v69
	v_rcp_f32_e32 v70, v70
	v_rcp_f32_e32 v71, v71
	s_waitcnt lgkmcnt(0)
	v_rcp_f32_e32 v76, v64
	v_rcp_f32_e32 v77, v65
	v_rcp_f32_e32 v78, v66
	v_rcp_f32_e32 v79, v67
	ds_read_b128 v[64:67], v80 offset:96
	v_pk_mul_f32 v[48:49], v[48:49], v[72:73]
	v_pk_mul_f32 v[50:51], v[50:51], v[74:75]
	v_pk_mul_f32 v[32:33], v[32:33], v[72:73]
	v_pk_mul_f32 v[34:35], v[34:35], v[74:75]
	s_waitcnt lgkmcnt(0)
	v_rcp_f32_e32 v64, v64
	v_rcp_f32_e32 v65, v65
	v_rcp_f32_e32 v66, v66
	v_rcp_f32_e32 v67, v67
	v_pk_mul_f32 v[16:17], v[16:17], v[72:73]
	v_pk_mul_f32 v[18:19], v[18:19], v[74:75]
	v_pk_mul_f32 v[0:1], v[0:1], v[72:73]
	v_pk_mul_f32 v[2:3], v[2:3], v[74:75]
	flat_store_dwordx4 v[112:113], v[48:51]
	flat_store_dwordx4 v[112:113], v[32:35] offset:64
	flat_store_dwordx4 v[112:113], v[16:19] offset:128
	v_pk_mul_f32 v[48:49], v[52:53], v[68:69]
	v_pk_mul_f32 v[50:51], v[54:55], v[70:71]
	v_pk_mul_f32 v[32:33], v[36:37], v[68:69]
	v_pk_mul_f32 v[34:35], v[38:39], v[70:71]
	v_pk_mul_f32 v[16:17], v[20:21], v[68:69]
	v_pk_mul_f32 v[18:19], v[22:23], v[70:71]
	flat_store_dwordx4 v[112:113], v[0:3] offset:192
	flat_store_dwordx4 v[112:113], v[48:51] offset:16
	flat_store_dwordx4 v[112:113], v[32:35] offset:80
	v_pk_mul_f32 v[0:1], v[4:5], v[68:69]
	v_pk_mul_f32 v[2:3], v[6:7], v[70:71]
	v_pk_mul_f32 v[48:49], v[56:57], v[76:77]
	v_pk_mul_f32 v[50:51], v[58:59], v[78:79]
	v_pk_mul_f32 v[32:33], v[40:41], v[76:77]
	v_pk_mul_f32 v[34:35], v[42:43], v[78:79]
	flat_store_dwordx4 v[112:113], v[16:19] offset:144
	flat_store_dwordx4 v[112:113], v[0:3] offset:208
	flat_store_dwordx4 v[112:113], v[48:51] offset:32
	v_pk_mul_f32 v[16:17], v[24:25], v[76:77]
	v_pk_mul_f32 v[18:19], v[26:27], v[78:79]
	v_pk_mul_f32 v[0:1], v[8:9], v[76:77]
	v_pk_mul_f32 v[2:3], v[10:11], v[78:79]
	v_pk_mul_f32 v[48:49], v[60:61], v[64:65]
	v_pk_mul_f32 v[50:51], v[62:63], v[66:67]
	flat_store_dwordx4 v[112:113], v[32:35] offset:96
	flat_store_dwordx4 v[112:113], v[16:19] offset:160
	flat_store_dwordx4 v[112:113], v[0:3] offset:224
	v_pk_mul_f32 v[32:33], v[44:45], v[64:65]
	v_pk_mul_f32 v[34:35], v[46:47], v[66:67]
	v_pk_mul_f32 v[16:17], v[28:29], v[64:65]
	v_pk_mul_f32 v[18:19], v[30:31], v[66:67]
	v_pk_mul_f32 v[0:1], v[12:13], v[64:65]
	v_pk_mul_f32 v[2:3], v[14:15], v[66:67]
	v_mov_b32_e32 v4, v218
	flat_store_dwordx4 v[112:113], v[48:51] offset:48
	flat_store_dwordx4 v[112:113], v[32:35] offset:112
	flat_store_dwordx4 v[112:113], v[16:19] offset:176
	flat_store_dwordx4 v[112:113], v[0:3] offset:240
	v_mov_b32_e32 v14, v185
	v_and_b32_e32 v6, 31, v4
	v_and_b32_e32 v0, 0x3fffffc0, v4
	v_lshl_add_u32 v122, v0, 2, s4
	v_ashrrev_i32_e32 v0, 6, v4
	v_lshrrev_b32_e32 v7, 1, v4
	v_readfirstlane_b32 s0, v0
	v_lshl_or_b32 v0, v0, 5, v6
	v_ashrrev_i32_e32 v1, 31, v0
	v_lshlrev_b64 v[0:1], 10, v[0:1]
	v_and_b32_e32 v5, 63, v4
	v_lshl_add_u64 v[0:1], s[30:31], 0, v[0:1]
	v_and_b32_e32 v184, 16, v7
	v_lshl_add_u64 v[0:1], v[0:1], 0, v[184:185]
	s_lshl_b32 s1, s0, 10
	v_lshlrev_b32_e32 v8, 4, v5
	global_load_dwordx4 v[96:99], v[0:1], off offset:128
	global_load_dwordx4 v[100:103], v[0:1], off offset:160
	global_load_dwordx4 v[104:107], v[0:1], off offset:192
	global_load_dwordx4 v[108:111], v[0:1], off offset:224
	v_or_b32_e32 v0, s1, v8
	v_ashrrev_i32_e32 v1, 31, v0
	v_lshrrev_b32_e32 v1, 25, v1
	v_add_u32_e32 v1, v0, v1
	v_lshlrev_b32_e32 v9, 3, v5
	s_lshl_b32 s0, s0, 6
	v_ashrrev_i32_e32 v2, 7, v1
	v_and_b32_e32 v1, 0xffffff80, v1
	v_and_b32_e32 v3, 32, v4
	s_and_b32 s0, s0, 64
	v_and_b32_e32 v10, 24, v9
	v_sub_u32_e32 v0, v0, v1
	v_or3_b32 v3, v10, v3, s0
	s_ashr_i32 s0, s1, 8
	v_ashrrev_i32_e32 v0, 4, v0
	v_lshrrev_b32_e32 v1, 1, v2
	s_and_b32 s4, s0, 0x7ffff0
	s_lshr_b32 s0, s0, 1
	v_bitop3_b32 v0, v1, v0, 7 bitop3:0x6c
	v_bfe_u32 v1, v4, 2, 2
	s_and_b32 s0, s0, 4
	v_and_or_b32 v1, v7, 8, v1
	s_or_b32 s0, s4, s0
	v_or_b32_e32 v10, s0, v1
	s_add_i32 s0, s1, 0x2000
	s_ashr_i32 s0, s0, 8
	s_and_b32 s4, s0, 0x7ffff0
	s_lshr_b32 s0, s0, 1
	s_and_b32 s0, s0, 4
	s_or_b32 s0, s4, s0
	v_or_b32_e32 v1, s0, v1
	v_lshl_or_b32 v116, v1, 9, v3
	v_lshlrev_b32_e32 v1, 9, v2
	v_lshl_add_u32 v0, v0, 3, v1
	v_ashrrev_i32_e32 v1, 31, v0
	v_lshlrev_b64 v[0:1], 1, v[0:1]
	v_lshl_or_b32 v114, v10, 9, v3
	v_lshl_add_u64 v[2:3], s[68:69], 0, v[0:1]
	s_add_i32 s4, s1, 0
	v_lshl_add_u64 v[2:3], v[2:3], 0, s[78:79]
	s_add_i32 m0, s4, 0x8000
	v_ashrrev_i32_e32 v115, 31, v114
	s_waitcnt lgkmcnt(0)
	s_barrier
	global_load_lds_dwordx4 v[2:3], off
	v_lshl_add_u64 v[2:3], v[114:115], 1, s[34:35]
	s_mov_b32 m0, s4
	v_ashrrev_i32_e32 v117, 31, v116
	global_load_lds_dwordx4 v[2:3], off
	v_lshl_add_u64 v[2:3], v[116:117], 1, s[34:35]
	s_add_i32 m0, s4, 0x2000
	s_cmp_lg_u32 0, -1
	global_load_lds_dwordx4 v[2:3], off
	s_cselect_b32 s0, 0, 0
	v_lshlrev_b32_e32 v10, 1, v4
	v_lshlrev_b32_e32 v4, 3, v4
	s_add_i32 s1, s0, 0x8000
	v_and_b32_e32 v4, 0x70, v4
	v_lshl_add_u32 v124, v6, 7, s1
	s_movk_i32 s1, 0x60
	v_and_b32_e32 v3, 32, v10
	v_bitop3_b32 v128, v184, v4, s1 bitop3:0x36
	s_movk_i32 s1, 0x118
	v_and_b32_e32 v2, 0xc0, v8
	s_waitcnt vmcnt(0)
	v_lshl_add_u64 v[118:119], s[24:25], 0, v[0:1]
	v_and_or_b32 v0, v9, s1, v3
	v_mov_b32_e32 v15, v185
	v_bitop3_b32 v125, v7, v4, 16 bitop3:0x6c
	v_bitop3_b32 v126, v184, v4, 32 bitop3:0x36
	v_bitop3_b32 v127, v184, v4, 64 bitop3:0x36
	v_cmp_gt_u32_e64 s[6:7], 32, v5
	v_lshl_add_u32 v123, v6, 2, v122
	v_add3_u32 v129, v2, s0, v0
	v_mov_b32_e32 v0, v185
	v_mov_b32_e32 v1, v185
	v_mov_b32_e32 v2, v185
	v_mov_b32_e32 v3, v185
	v_mov_b32_e32 v4, v185
	v_mov_b32_e32 v5, v185
	v_mov_b32_e32 v6, v185
	v_mov_b32_e32 v7, v185
	v_mov_b32_e32 v8, v185
	v_mov_b32_e32 v9, v185
	v_mov_b32_e32 v10, v185
	v_mov_b32_e32 v11, v185
	v_mov_b32_e32 v12, v185
	v_mov_b32_e32 v13, v185
	v_mov_b64_e32 v[30:31], v[14:15]
	v_mov_b64_e32 v[46:47], v[14:15]
	v_mov_b64_e32 v[62:63], v[14:15]
	v_mov_b64_e32 v[28:29], v[12:13]
	v_mov_b64_e32 v[26:27], v[10:11]
	v_mov_b64_e32 v[24:25], v[8:9]
	v_mov_b64_e32 v[22:23], v[6:7]
	v_mov_b64_e32 v[20:21], v[4:5]
	v_mov_b64_e32 v[18:19], v[2:3]
	v_mov_b64_e32 v[16:17], v[0:1]
	v_mov_b64_e32 v[44:45], v[12:13]
	v_mov_b64_e32 v[42:43], v[10:11]
	v_mov_b64_e32 v[40:41], v[8:9]
	v_mov_b64_e32 v[38:39], v[6:7]
	v_mov_b64_e32 v[36:37], v[4:5]
	v_mov_b64_e32 v[34:35], v[2:3]
	v_mov_b64_e32 v[32:33], v[0:1]
	v_mov_b64_e32 v[60:61], v[12:13]
	v_mov_b64_e32 v[58:59], v[10:11]
	v_mov_b64_e32 v[56:57], v[8:9]
	v_mov_b64_e32 v[54:55], v[6:7]
	v_mov_b64_e32 v[52:53], v[4:5]
	v_mov_b64_e32 v[50:51], v[2:3]
	v_mov_b64_e32 v[48:49], v[0:1]
	v_mov_b32_e32 v160, 0x80000000
	v_mov_b32_e32 v161, 0x80000000
	v_mov_b32_e32 v162, 0x80000000
	v_mov_b32_e32 v163, 0x80000000
	v_mov_b32_e32 v164, 0x80000000
	v_mov_b32_e32 v165, 0x80000000
	v_mov_b32_e32 v166, 0x80000000
	v_mov_b32_e32 v167, 0x80000000
	v_mov_b32_e32 v168, 0x80000000
	v_mov_b32_e32 v169, 0x80000000
	v_mov_b32_e32 v170, 0x80000000
	v_mov_b32_e32 v171, 0x80000000
	v_mov_b32_e32 v172, 0x80000000
	v_mov_b32_e32 v173, 0x80000000
	v_mov_b32_e32 v174, 0x80000000
	v_mov_b32_e32 v175, 0x80000000
	v_readlane_b32 s54, v254, 48
	s_waitcnt vmcnt(0) lgkmcnt(0)
	s_barrier
	s_and_b32 s53, s5, 1
	v_add_u32_e32 v120, v124, v125
	ds_read_b128 v[132:135], v120 offset:0
	ds_read_b128 v[136:139], v120 offset:0x1000
	s_cmp_eq_u32 s5, 31
	s_movk_i32 s0, 0x2000
	s_cbranch_scc1 .LBB0_152

.LBB0_152:
	v_add_u32_e32 v80, s0, v124
	v_add_u32_e32 v82, v80, v126
	ds_read_b128 v[140:143], v82 offset:0
	ds_read_b128 v[146:149], v82 offset:0x1000
	s_waitcnt lgkmcnt(2)
	v_add_u32_e32 v120, v80, v127
	v_add_u32_e32 v150, v80, v128
	v_mfma_f32_32x32x16_bf16 v[80:95], v[132:135], v[96:99], v[160:175]
	ds_read_b128 v[132:135], v120 offset:0
	v_mfma_f32_32x32x16_bf16 v[64:79], v[136:139], v[96:99], v[160:175]
	ds_read_b128 v[136:139], v120 offset:0x1000
	s_waitcnt lgkmcnt(2)
	v_mfma_f32_32x32x16_bf16 v[80:95], v[140:143], v[100:103], v[80:95]
	ds_read_b128 v[140:143], v150 offset:0
	v_mfma_f32_32x32x16_bf16 v[64:79], v[146:149], v[100:103], v[64:79]
	ds_read_b128 v[146:149], v150 offset:0x1000
	s_waitcnt lgkmcnt(2)
	v_mfma_f32_32x32x16_bf16 v[80:95], v[132:135], v[104:107], v[80:95]
	s_waitcnt lgkmcnt(0)
	v_mfma_f32_32x32x16_bf16 v[64:79], v[136:139], v[104:107], v[64:79]
	v_mfma_f32_32x32x16_bf16 v[80:95], v[140:143], v[108:111], v[80:95]
	s_cmp_eq_u32 s5, 0
	s_cselect_b64 s[24:25], -1, 0
	s_cmp_lg_u32 s5, 0
	v_mfma_f32_32x32x16_bf16 v[64:79], v[146:149], v[108:111], v[64:79]
	s_nop 7
	v_max_f32_e32 v120, v80, v81
	v_max3_f32 v120, v120, v82, v83
	v_max3_f32 v120, v120, v84, v85
	v_max3_f32 v120, v120, v86, v87
	v_max3_f32 v120, v120, v88, v89
	v_max3_f32 v120, v120, v90, v91
	v_max3_f32 v120, v120, v92, v93
	v_max3_f32 v120, v120, v94, v95
	v_max3_f32 v120, v120, v64, v65
	v_max3_f32 v120, v120, v66, v67
	v_max3_f32 v120, v120, v68, v69
	v_max3_f32 v120, v120, v70, v71
	v_max3_f32 v120, v120, v72, v73
	v_max3_f32 v120, v120, v74, v75
	v_max3_f32 v120, v120, v76, v77
	v_max3_f32 v120, v120, v78, v79
	s_cbranch_scc0 .Lmx2_first
	v_cmp_ge_f32_e32 vcc, s62, v120
	s_cmp_lg_u64 vcc, exec
	s_mov_b64 s[34:35], 0
	s_mov_b64 s[30:31], 0
	s_cbranch_scc1 .Lmx2_slow
	v_mov_b32_e32 v132, 1.0
	s_branch .LBB0_164
.Lmx2_first:
	v_mov_b32_e32 v132, v120
	s_nop 1
	v_permlane32_swap_b32_e32 v120, v132
	v_max_f32_e32 v132, v120, v132
	s_branch .LBB0_157

.LBB0_164:
	v_exp_f32_e32 v80, v80
	v_exp_f32_e32 v81, v81
	v_exp_f32_e32 v82, v82
	v_exp_f32_e32 v83, v83
	v_exp_f32_e32 v84, v84
	v_exp_f32_e32 v120, v64
	v_exp_f32_e32 v85, v85
	v_add_f32_e32 v64, v81, v80
	v_exp_f32_e32 v86, v86
	v_add_f32_e32 v64, v82, v64
	v_exp_f32_e32 v87, v87
	v_add_f32_e32 v64, v83, v64
	v_exp_f32_e32 v88, v88
	v_add_f32_e32 v64, v84, v64
	v_exp_f32_e32 v89, v89
	v_add_f32_e32 v64, v85, v64
	v_exp_f32_e32 v90, v90
	v_add_f32_e32 v64, v86, v64
	v_exp_f32_e32 v91, v91
	v_add_f32_e32 v64, v87, v64
	v_exp_f32_e32 v92, v92
	v_add_f32_e32 v64, v88, v64
	v_exp_f32_e32 v93, v93
	v_add_f32_e32 v64, v89, v64
	v_exp_f32_e32 v94, v94
	v_add_f32_e32 v64, v90, v64
	v_exp_f32_e32 v95, v95
	v_add_f32_e32 v64, v91, v64
	v_add_f32_e32 v64, v92, v64
	v_exp_f32_e32 v65, v65
	v_add_f32_e32 v64, v93, v64
	v_exp_f32_e32 v133, v66
	v_add_f32_e32 v64, v94, v64
	v_exp_f32_e32 v134, v67
	v_add_f32_e32 v64, v95, v64
	v_exp_f32_e32 v135, v68
	v_add_f32_e32 v64, v120, v64
	v_exp_f32_e32 v136, v69
	v_add_f32_e32 v64, v65, v64
	v_exp_f32_e32 v137, v70
	v_add_f32_e32 v64, v133, v64
	v_exp_f32_e32 v138, v71
	v_add_f32_e32 v64, v134, v64
	v_exp_f32_e32 v139, v72
	v_add_f32_e32 v64, v135, v64
	v_exp_f32_e32 v140, v73
	v_add_f32_e32 v64, v136, v64
	v_exp_f32_e32 v141, v74
	v_add_f32_e32 v64, v137, v64
	v_exp_f32_e32 v142, v75
	v_add_f32_e32 v64, v138, v64
	v_exp_f32_e32 v143, v76
	v_add_f32_e32 v64, v139, v64
	v_exp_f32_e32 v146, v77
	v_add_f32_e32 v64, v140, v64
	v_exp_f32_e32 v147, v78
	v_add_f32_e32 v64, v141, v64
	v_exp_f32_e32 v148, v79
	v_add_f32_e32 v64, v142, v64
	v_add_f32_e32 v64, v143, v64
	v_add_f32_e32 v64, v146, v64
	v_add_f32_e32 v64, v147, v64
	v_add_f32_e32 v64, v148, v64
	s_add_i32 s5, s5, 1
	v_fma_f32 v131, v131, v132, v64
	v_cvt_pk_bf16_f32 v66, v80, v81
	v_cvt_pk_bf16_f32 v67, v82, v83
	v_cvt_pk_bf16_f32 v68, v84, v85
	v_cvt_pk_bf16_f32 v69, v86, v87
	v_cvt_pk_bf16_f32 v70, v88, v89
	v_cvt_pk_bf16_f32 v71, v90, v91
	v_cvt_pk_bf16_f32 v72, v92, v93
	v_cvt_pk_bf16_f32 v73, v94, v95
	v_cvt_pk_bf16_f32 v74, v120, v65
	v_cvt_pk_bf16_f32 v75, v133, v134
	v_cvt_pk_bf16_f32 v76, v135, v136
	v_cvt_pk_bf16_f32 v77, v137, v138
	v_cvt_pk_bf16_f32 v78, v139, v140
	v_cvt_pk_bf16_f32 v79, v141, v142
	v_cvt_pk_bf16_f32 v80, v143, v146
	v_cvt_pk_bf16_f32 v81, v147, v148
	s_nop 0
	v_permlane32_swap_b32_e32 v66, v68
	v_permlane32_swap_b32_e32 v67, v69
	v_permlane32_swap_b32_e32 v70, v72
	v_permlane32_swap_b32_e32 v71, v73
	v_permlane32_swap_b32_e32 v74, v76
	v_permlane32_swap_b32_e32 v75, v77
	v_permlane32_swap_b32_e32 v78, v80
	v_permlane32_swap_b32_e32 v79, v81
	v_lshl_add_u32 v65, s53, 14, v129
	ds_read_b64_tr_b16 v[82:83], v65 offset:0
	ds_read_b64_tr_b16 v[84:85], v65 offset:0x800
	ds_read_b64_tr_b16 v[86:87], v65 offset:0x1000
	ds_read_b64_tr_b16 v[88:89], v65 offset:0x1800
	ds_read_b64_tr_b16 v[90:91], v65 offset:0x2000
	ds_read_b64_tr_b16 v[92:93], v65 offset:0x2800
	ds_read_b64_tr_b16 v[132:133], v65 offset:0x3000
	ds_read_b64_tr_b16 v[134:135], v65 offset:0x3800
	ds_read_b64_tr_b16 v[136:137], v65 offset:0x200
	ds_read_b64_tr_b16 v[138:139], v65 offset:0xa00
	ds_read_b64_tr_b16 v[140:141], v65 offset:0x1200
	ds_read_b64_tr_b16 v[142:143], v65 offset:0x1a00
	ds_read_b64_tr_b16 v[146:147], v65 offset:0x2200
	ds_read_b64_tr_b16 v[148:149], v65 offset:0x2a00
	ds_read_b64_tr_b16 v[150:151], v65 offset:0x3200
	ds_read_b64_tr_b16 v[152:153], v65 offset:0x3a00
	s_waitcnt lgkmcnt(8)
	s_nop 0
	v_mfma_f32_32x32x16_bf16 v[48:63], v[66:69], v[82:85], v[48:63]
	ds_read_b64_tr_b16 v[82:83], v65 offset:0x400
	ds_read_b64_tr_b16 v[84:85], v65 offset:0xc00
	v_mfma_f32_32x32x16_bf16 v[48:63], v[70:73], v[86:89], v[48:63]
	ds_read_b64_tr_b16 v[86:87], v65 offset:0x1400
	ds_read_b64_tr_b16 v[88:89], v65 offset:0x1c00
	v_mfma_f32_32x32x16_bf16 v[48:63], v[74:77], v[90:93], v[48:63]
	ds_read_b64_tr_b16 v[90:91], v65 offset:0x2400
	ds_read_b64_tr_b16 v[92:93], v65 offset:0x2c00
	v_mfma_f32_32x32x16_bf16 v[48:63], v[78:81], v[132:135], v[48:63]
	ds_read_b64_tr_b16 v[132:133], v65 offset:0x3400
	ds_read_b64_tr_b16 v[134:135], v65 offset:0x3c00
	s_waitcnt lgkmcnt(8)
	v_mfma_f32_32x32x16_bf16 v[32:47], v[66:69], v[136:139], v[32:47]
	ds_read_b64_tr_b16 v[136:137], v65 offset:0x600
	ds_read_b64_tr_b16 v[138:139], v65 offset:0xe00
	v_mfma_f32_32x32x16_bf16 v[32:47], v[70:73], v[140:143], v[32:47]
	ds_read_b64_tr_b16 v[140:141], v65 offset:0x1600
	ds_read_b64_tr_b16 v[142:143], v65 offset:0x1e00
	v_mfma_f32_32x32x16_bf16 v[32:47], v[74:77], v[146:149], v[32:47]
	ds_read_b64_tr_b16 v[146:147], v65 offset:0x2600
	ds_read_b64_tr_b16 v[148:149], v65 offset:0x2e00
	v_mfma_f32_32x32x16_bf16 v[32:47], v[78:81], v[150:153], v[32:47]
	ds_read_b64_tr_b16 v[150:151], v65 offset:0x3600
	ds_read_b64_tr_b16 v[152:153], v65 offset:0x3e00
	s_waitcnt lgkmcnt(8)
	v_mfma_f32_32x32x16_bf16 v[16:31], v[66:69], v[82:85], v[16:31]
	s_waitcnt lgkmcnt(0)
	v_mfma_f32_32x32x16_bf16 v[16:31], v[70:73], v[86:89], v[16:31]
	v_mfma_f32_32x32x16_bf16 v[16:31], v[74:77], v[90:93], v[16:31]
	v_mfma_f32_32x32x16_bf16 v[16:31], v[78:81], v[132:135], v[16:31]
	v_mfma_f32_32x32x16_bf16 v[0:15], v[66:69], v[136:139], v[0:15]
	s_waitcnt vmcnt(0)
	s_add_i32 s67, s67, 0x8000
	s_cmp_eq_u32 s5, 32
	s_waitcnt vmcnt(0) lgkmcnt(0)
	s_barrier
	s_and_b32 s1, s5, 1
	s_lshl_b32 s1, s1, 13
	v_add3_u32 v120, v124, v125, s1
	ds_read_b128 v[132:135], v120 offset:0
	ds_read_b128 v[136:139], v120 offset:0x1000
	s_cmp_eq_u32 s5, 32
	v_mfma_f32_32x32x16_bf16 v[0:15], v[70:73], v[140:143], v[0:15]
	v_mfma_f32_32x32x16_bf16 v[0:15], v[74:77], v[146:149], v[0:15]
	v_mfma_f32_32x32x16_bf16 v[0:15], v[78:81], v[150:153], v[0:15]
	s_cbranch_scc1 .LBB0_166
	s_and_b32 s53, s5, 1
	s_cmp_eq_u32 s5, 31
	s_movk_i32 s0, 0x2000
	s_cbranch_scc0 .LBB0_151
	s_branch .LBB0_152
.LBB0_166:
	v_mov_b32_e32 v66, v131
	s_nop 1
	v_permlane32_swap_b32_e32 v131, v66
	v_add_f32_e32 v64, v131, v66
	s_and_saveexec_b64 s[0:1], s[6:7]
	v_readlane_b32 s53, v254, 49
	ds_write_b32 v123, v64
	s_or_b64 exec, exec, s[0:1]
	s_waitcnt lgkmcnt(0)
	global_load_dwordx4 v[68:71], v[112:113], off
	global_load_dwordx4 v[72:75], v[112:113], off offset:16
	global_load_dwordx4 v[76:79], v[112:113], off offset:32
	global_load_dwordx4 v[80:83], v[112:113], off offset:48
	global_load_dwordx4 v[84:87], v[112:113], off offset:64
	global_load_dwordx4 v[88:91], v[112:113], off offset:80
	global_load_dwordx4 v[92:95], v[112:113], off offset:96
	global_load_dwordx4 v[96:99], v[112:113], off offset:112
	global_load_dwordx4 v[100:103], v[112:113], off offset:128
	global_load_dwordx4 v[104:107], v[112:113], off offset:144
	global_load_dwordx4 v[108:111], v[112:113], off offset:160
	global_load_dwordx4 v[130:133], v[112:113], off offset:176
	global_load_dwordx4 v[134:137], v[112:113], off offset:192
	global_load_dwordx4 v[138:141], v[112:113], off offset:208
	global_load_dwordx4 v[146:149], v[112:113], off offset:224
	global_load_dwordx4 v[150:153], v[112:113], off offset:240
	v_and_b32_e32 v66, 31, v121
	v_lshlrev_b32_e32 v67, 2, v66
	global_load_dword v154, v67, s[10:11]
	global_load_dword v156, v67, s[10:11] offset:128
	global_load_dword v158, v67, s[10:11] offset:256
	global_load_dword v178, v67, s[10:11] offset:384
	v_add_u32_e32 v65, v122, v184
	s_waitcnt lgkmcnt(0)
	ds_read_b128 v[160:163], v65
	ds_read_b128 v[164:167], v65 offset:32
	ds_read_b128 v[168:171], v65 offset:64
	ds_read_b128 v[172:175], v65 offset:96
	v_ashrrev_i32_e32 v176, 1, v121
	v_and_b32_e32 v176, 0xffffffe0, v176
	v_ashrrev_i32_e32 v177, 31, v176
	v_lshl_add_u64 v[176:177], s[22:23], 0, v[176:177]
	v_lshrrev_b32_e32 v180, 3, v121
	v_and_or_b32 v176, v180, 4, v176
	v_lshlrev_b64 v[176:177], 11, v[176:177]
	v_lshl_add_u64 v[176:177], s[8:9], 0, v[176:177]
	s_lshl_b32 s88, s65, 1
	v_lshl_add_u64 v[176:177], v[176:177], 0, s[88:89]
	v_lshlrev_b32_e32 v184, 1, v66
	v_lshl_add_u64 v[176:177], v[176:177], 0, v[184:185]
	s_waitcnt lgkmcnt(0)
	v_rcp_f32_e32 v160, v160
	v_rcp_f32_e32 v161, v161
	v_rcp_f32_e32 v162, v162
	v_rcp_f32_e32 v163, v163
	v_rcp_f32_e32 v164, v164
	v_rcp_f32_e32 v165, v165
	v_rcp_f32_e32 v166, v166
	v_rcp_f32_e32 v167, v167
	v_rcp_f32_e32 v168, v168
	v_rcp_f32_e32 v169, v169
	v_rcp_f32_e32 v170, v170
	v_rcp_f32_e32 v171, v171
	v_rcp_f32_e32 v172, v172
	v_rcp_f32_e32 v173, v173
	v_rcp_f32_e32 v174, v174
	v_rcp_f32_e32 v175, v175
	v_pk_mul_f32 v[48:49], v[48:49], v[160:161]
	v_pk_mul_f32 v[50:51], v[50:51], v[162:163]
	v_pk_mul_f32 v[52:53], v[52:53], v[164:165]
	v_pk_mul_f32 v[54:55], v[54:55], v[166:167]
	v_pk_mul_f32 v[56:57], v[56:57], v[168:169]
	v_pk_mul_f32 v[58:59], v[58:59], v[170:171]
	v_pk_mul_f32 v[60:61], v[60:61], v[172:173]
	v_pk_mul_f32 v[62:63], v[62:63], v[174:175]
	v_pk_mul_f32 v[32:33], v[32:33], v[160:161]
	v_pk_mul_f32 v[34:35], v[34:35], v[162:163]
	v_pk_mul_f32 v[36:37], v[36:37], v[164:165]
	v_pk_mul_f32 v[38:39], v[38:39], v[166:167]
	v_pk_mul_f32 v[40:41], v[40:41], v[168:169]
	v_pk_mul_f32 v[42:43], v[42:43], v[170:171]
	v_pk_mul_f32 v[44:45], v[44:45], v[172:173]
	v_pk_mul_f32 v[46:47], v[46:47], v[174:175]
	v_pk_mul_f32 v[16:17], v[16:17], v[160:161]
	v_pk_mul_f32 v[18:19], v[18:19], v[162:163]
	v_pk_mul_f32 v[20:21], v[20:21], v[164:165]
	v_pk_mul_f32 v[22:23], v[22:23], v[166:167]
	v_pk_mul_f32 v[24:25], v[24:25], v[168:169]
	v_pk_mul_f32 v[26:27], v[26:27], v[170:171]
	v_pk_mul_f32 v[28:29], v[28:29], v[172:173]
	v_pk_mul_f32 v[30:31], v[30:31], v[174:175]
	v_pk_mul_f32 v[0:1], v[0:1], v[160:161]
	v_pk_mul_f32 v[2:3], v[2:3], v[162:163]
	v_pk_mul_f32 v[4:5], v[4:5], v[164:165]
	v_pk_mul_f32 v[6:7], v[6:7], v[166:167]
	v_pk_mul_f32 v[8:9], v[8:9], v[168:169]
	v_pk_mul_f32 v[10:11], v[10:11], v[170:171]
	v_pk_mul_f32 v[12:13], v[12:13], v[172:173]
	v_pk_mul_f32 v[14:15], v[14:15], v[174:175]
	s_waitcnt vmcnt(0)
	v_mul_f32_e32 v154, v157, v154
	v_mul_f32_e32 v156, v157, v156
	v_mul_f32_e32 v158, v157, v158
	v_mul_f32_e32 v178, v157, v178
	v_pk_fma_f32 v[48:49], v[144:145], v[48:49], v[68:69] neg_lo:[1,0,0] neg_hi:[1,0,0]
	v_pk_fma_f32 v[50:51], v[144:145], v[50:51], v[70:71] neg_lo:[1,0,0] neg_hi:[1,0,0]
	v_pk_fma_f32 v[52:53], v[144:145], v[52:53], v[72:73] neg_lo:[1,0,0] neg_hi:[1,0,0]
	v_pk_fma_f32 v[54:55], v[144:145], v[54:55], v[74:75] neg_lo:[1,0,0] neg_hi:[1,0,0]
	v_pk_fma_f32 v[56:57], v[144:145], v[56:57], v[76:77] neg_lo:[1,0,0] neg_hi:[1,0,0]
	v_pk_fma_f32 v[58:59], v[144:145], v[58:59], v[78:79] neg_lo:[1,0,0] neg_hi:[1,0,0]
	v_pk_fma_f32 v[60:61], v[144:145], v[60:61], v[80:81] neg_lo:[1,0,0] neg_hi:[1,0,0]
	v_pk_fma_f32 v[62:63], v[144:145], v[62:63], v[82:83] neg_lo:[1,0,0] neg_hi:[1,0,0]
	v_pk_fma_f32 v[32:33], v[144:145], v[32:33], v[84:85] neg_lo:[1,0,0] neg_hi:[1,0,0]
	v_pk_fma_f32 v[34:35], v[144:145], v[34:35], v[86:87] neg_lo:[1,0,0] neg_hi:[1,0,0]
	v_pk_fma_f32 v[36:37], v[144:145], v[36:37], v[88:89] neg_lo:[1,0,0] neg_hi:[1,0,0]
	v_pk_fma_f32 v[38:39], v[144:145], v[38:39], v[90:91] neg_lo:[1,0,0] neg_hi:[1,0,0]
	v_pk_fma_f32 v[40:41], v[144:145], v[40:41], v[92:93] neg_lo:[1,0,0] neg_hi:[1,0,0]
	v_pk_fma_f32 v[42:43], v[144:145], v[42:43], v[94:95] neg_lo:[1,0,0] neg_hi:[1,0,0]
	v_pk_fma_f32 v[44:45], v[144:145], v[44:45], v[96:97] neg_lo:[1,0,0] neg_hi:[1,0,0]
	v_pk_fma_f32 v[46:47], v[144:145], v[46:47], v[98:99] neg_lo:[1,0,0] neg_hi:[1,0,0]
	v_pk_fma_f32 v[16:17], v[144:145], v[16:17], v[100:101] neg_lo:[1,0,0] neg_hi:[1,0,0]
	v_pk_fma_f32 v[18:19], v[144:145], v[18:19], v[102:103] neg_lo:[1,0,0] neg_hi:[1,0,0]
	v_pk_fma_f32 v[20:21], v[144:145], v[20:21], v[104:105] neg_lo:[1,0,0] neg_hi:[1,0,0]
	v_pk_fma_f32 v[22:23], v[144:145], v[22:23], v[106:107] neg_lo:[1,0,0] neg_hi:[1,0,0]
	v_pk_fma_f32 v[24:25], v[144:145], v[24:25], v[108:109] neg_lo:[1,0,0] neg_hi:[1,0,0]
	v_pk_fma_f32 v[26:27], v[144:145], v[26:27], v[110:111] neg_lo:[1,0,0] neg_hi:[1,0,0]
	v_pk_fma_f32 v[28:29], v[144:145], v[28:29], v[130:131] neg_lo:[1,0,0] neg_hi:[1,0,0]
	v_pk_fma_f32 v[30:31], v[144:145], v[30:31], v[132:133] neg_lo:[1,0,0] neg_hi:[1,0,0]
	v_pk_fma_f32 v[0:1], v[144:145], v[0:1], v[134:135] neg_lo:[1,0,0] neg_hi:[1,0,0]
	v_pk_fma_f32 v[2:3], v[144:145], v[2:3], v[136:137] neg_lo:[1,0,0] neg_hi:[1,0,0]
	v_pk_fma_f32 v[4:5], v[144:145], v[4:5], v[138:139] neg_lo:[1,0,0] neg_hi:[1,0,0]
	v_pk_fma_f32 v[6:7], v[144:145], v[6:7], v[140:141] neg_lo:[1,0,0] neg_hi:[1,0,0]
	v_pk_fma_f32 v[8:9], v[144:145], v[8:9], v[146:147] neg_lo:[1,0,0] neg_hi:[1,0,0]
	v_pk_fma_f32 v[10:11], v[144:145], v[10:11], v[148:149] neg_lo:[1,0,0] neg_hi:[1,0,0]
	v_pk_fma_f32 v[12:13], v[144:145], v[12:13], v[150:151] neg_lo:[1,0,0] neg_hi:[1,0,0]
	v_pk_fma_f32 v[14:15], v[144:145], v[14:15], v[152:153] neg_lo:[1,0,0] neg_hi:[1,0,0]
	v_pk_mul_f32 v[68:69], v[48:49], v[48:49]
	v_pk_mul_f32 v[70:71], v[50:51], v[50:51]
	v_pk_mul_f32 v[72:73], v[52:53], v[52:53]
	v_pk_mul_f32 v[74:75], v[54:55], v[54:55]
	v_pk_mul_f32 v[76:77], v[56:57], v[56:57]
	v_pk_mul_f32 v[78:79], v[58:59], v[58:59]
	v_pk_mul_f32 v[80:81], v[60:61], v[60:61]
	v_pk_mul_f32 v[82:83], v[62:63], v[62:63]
	v_pk_fma_f32 v[68:69], v[32:33], v[32:33], v[68:69]
	v_pk_fma_f32 v[70:71], v[34:35], v[34:35], v[70:71]
	v_pk_fma_f32 v[72:73], v[36:37], v[36:37], v[72:73]
	v_pk_fma_f32 v[74:75], v[38:39], v[38:39], v[74:75]
	v_pk_fma_f32 v[76:77], v[40:41], v[40:41], v[76:77]
	v_pk_fma_f32 v[78:79], v[42:43], v[42:43], v[78:79]
	v_pk_fma_f32 v[80:81], v[44:45], v[44:45], v[80:81]
	v_pk_fma_f32 v[82:83], v[46:47], v[46:47], v[82:83]
	v_pk_fma_f32 v[68:69], v[16:17], v[16:17], v[68:69]
	v_pk_fma_f32 v[70:71], v[18:19], v[18:19], v[70:71]
	v_pk_fma_f32 v[72:73], v[20:21], v[20:21], v[72:73]
	v_pk_fma_f32 v[74:75], v[22:23], v[22:23], v[74:75]
	v_pk_fma_f32 v[76:77], v[24:25], v[24:25], v[76:77]
	v_pk_fma_f32 v[78:79], v[26:27], v[26:27], v[78:79]
	v_pk_fma_f32 v[80:81], v[28:29], v[28:29], v[80:81]
	v_pk_fma_f32 v[82:83], v[30:31], v[30:31], v[82:83]
	v_pk_fma_f32 v[68:69], v[0:1], v[0:1], v[68:69]
	v_pk_fma_f32 v[70:71], v[2:3], v[2:3], v[70:71]
	v_pk_fma_f32 v[72:73], v[4:5], v[4:5], v[72:73]
	v_pk_fma_f32 v[74:75], v[6:7], v[6:7], v[74:75]
	v_pk_fma_f32 v[76:77], v[8:9], v[8:9], v[76:77]
	v_pk_fma_f32 v[78:79], v[10:11], v[10:11], v[78:79]
	v_pk_fma_f32 v[80:81], v[12:13], v[12:13], v[80:81]
	v_pk_fma_f32 v[82:83], v[14:15], v[14:15], v[82:83]
	v_add_f32_dpp v68, v68, v68 quad_perm:[1,0,3,2] row_mask:0xf bank_mask:0xf
	v_add_f32_dpp v69, v69, v69 quad_perm:[1,0,3,2] row_mask:0xf bank_mask:0xf
	v_add_f32_dpp v70, v70, v70 quad_perm:[1,0,3,2] row_mask:0xf bank_mask:0xf
	v_add_f32_dpp v71, v71, v71 quad_perm:[1,0,3,2] row_mask:0xf bank_mask:0xf
	v_add_f32_dpp v72, v72, v72 quad_perm:[1,0,3,2] row_mask:0xf bank_mask:0xf
	v_add_f32_dpp v73, v73, v73 quad_perm:[1,0,3,2] row_mask:0xf bank_mask:0xf
	v_add_f32_dpp v74, v74, v74 quad_perm:[1,0,3,2] row_mask:0xf bank_mask:0xf
	v_add_f32_dpp v75, v75, v75 quad_perm:[1,0,3,2] row_mask:0xf bank_mask:0xf
	v_add_f32_dpp v76, v76, v76 quad_perm:[1,0,3,2] row_mask:0xf bank_mask:0xf
	v_add_f32_dpp v77, v77, v77 quad_perm:[1,0,3,2] row_mask:0xf bank_mask:0xf
	v_add_f32_dpp v78, v78, v78 quad_perm:[1,0,3,2] row_mask:0xf bank_mask:0xf
	v_add_f32_dpp v79, v79, v79 quad_perm:[1,0,3,2] row_mask:0xf bank_mask:0xf
	v_add_f32_dpp v80, v80, v80 quad_perm:[1,0,3,2] row_mask:0xf bank_mask:0xf
	v_add_f32_dpp v81, v81, v81 quad_perm:[1,0,3,2] row_mask:0xf bank_mask:0xf
	v_add_f32_dpp v82, v82, v82 quad_perm:[1,0,3,2] row_mask:0xf bank_mask:0xf
	v_add_f32_dpp v83, v83, v83 quad_perm:[1,0,3,2] row_mask:0xf bank_mask:0xf
	v_add_f32_dpp v68, v68, v68 quad_perm:[2,3,0,1] row_mask:0xf bank_mask:0xf
	v_add_f32_dpp v69, v69, v69 quad_perm:[2,3,0,1] row_mask:0xf bank_mask:0xf
	v_add_f32_dpp v70, v70, v70 quad_perm:[2,3,0,1] row_mask:0xf bank_mask:0xf
	v_add_f32_dpp v71, v71, v71 quad_perm:[2,3,0,1] row_mask:0xf bank_mask:0xf
	v_add_f32_dpp v72, v72, v72 quad_perm:[2,3,0,1] row_mask:0xf bank_mask:0xf
	v_add_f32_dpp v73, v73, v73 quad_perm:[2,3,0,1] row_mask:0xf bank_mask:0xf
	v_add_f32_dpp v74, v74, v74 quad_perm:[2,3,0,1] row_mask:0xf bank_mask:0xf
	v_add_f32_dpp v75, v75, v75 quad_perm:[2,3,0,1] row_mask:0xf bank_mask:0xf
	v_add_f32_dpp v76, v76, v76 quad_perm:[2,3,0,1] row_mask:0xf bank_mask:0xf
	v_add_f32_dpp v77, v77, v77 quad_perm:[2,3,0,1] row_mask:0xf bank_mask:0xf
	v_add_f32_dpp v78, v78, v78 quad_perm:[2,3,0,1] row_mask:0xf bank_mask:0xf
	v_add_f32_dpp v79, v79, v79 quad_perm:[2,3,0,1] row_mask:0xf bank_mask:0xf
	v_add_f32_dpp v80, v80, v80 quad_perm:[2,3,0,1] row_mask:0xf bank_mask:0xf
	v_add_f32_dpp v81, v81, v81 quad_perm:[2,3,0,1] row_mask:0xf bank_mask:0xf
	v_add_f32_dpp v82, v82, v82 quad_perm:[2,3,0,1] row_mask:0xf bank_mask:0xf
	v_add_f32_dpp v83, v83, v83 quad_perm:[2,3,0,1] row_mask:0xf bank_mask:0xf
	v_add_f32_dpp v68, v68, v68 row_half_mirror row_mask:0xf bank_mask:0xf
	v_add_f32_dpp v69, v69, v69 row_half_mirror row_mask:0xf bank_mask:0xf
	v_add_f32_dpp v70, v70, v70 row_half_mirror row_mask:0xf bank_mask:0xf
	v_add_f32_dpp v71, v71, v71 row_half_mirror row_mask:0xf bank_mask:0xf
	v_add_f32_dpp v72, v72, v72 row_half_mirror row_mask:0xf bank_mask:0xf
	v_add_f32_dpp v73, v73, v73 row_half_mirror row_mask:0xf bank_mask:0xf
	v_add_f32_dpp v74, v74, v74 row_half_mirror row_mask:0xf bank_mask:0xf
	v_add_f32_dpp v75, v75, v75 row_half_mirror row_mask:0xf bank_mask:0xf
	v_add_f32_dpp v76, v76, v76 row_half_mirror row_mask:0xf bank_mask:0xf
	v_add_f32_dpp v77, v77, v77 row_half_mirror row_mask:0xf bank_mask:0xf
	v_add_f32_dpp v78, v78, v78 row_half_mirror row_mask:0xf bank_mask:0xf
	v_add_f32_dpp v79, v79, v79 row_half_mirror row_mask:0xf bank_mask:0xf
	v_add_f32_dpp v80, v80, v80 row_half_mirror row_mask:0xf bank_mask:0xf
	v_add_f32_dpp v81, v81, v81 row_half_mirror row_mask:0xf bank_mask:0xf
	v_add_f32_dpp v82, v82, v82 row_half_mirror row_mask:0xf bank_mask:0xf
	v_add_f32_dpp v83, v83, v83 row_half_mirror row_mask:0xf bank_mask:0xf
	v_add_f32_dpp v68, v68, v68 row_mirror row_mask:0xf bank_mask:0xf
	v_add_f32_dpp v69, v69, v69 row_mirror row_mask:0xf bank_mask:0xf
	v_add_f32_dpp v70, v70, v70 row_mirror row_mask:0xf bank_mask:0xf
	v_add_f32_dpp v71, v71, v71 row_mirror row_mask:0xf bank_mask:0xf
	v_add_f32_dpp v72, v72, v72 row_mirror row_mask:0xf bank_mask:0xf
	v_add_f32_dpp v73, v73, v73 row_mirror row_mask:0xf bank_mask:0xf
	v_add_f32_dpp v74, v74, v74 row_mirror row_mask:0xf bank_mask:0xf
	v_add_f32_dpp v75, v75, v75 row_mirror row_mask:0xf bank_mask:0xf
	v_add_f32_dpp v76, v76, v76 row_mirror row_mask:0xf bank_mask:0xf
	v_add_f32_dpp v77, v77, v77 row_mirror row_mask:0xf bank_mask:0xf
	v_add_f32_dpp v78, v78, v78 row_mirror row_mask:0xf bank_mask:0xf
	v_add_f32_dpp v79, v79, v79 row_mirror row_mask:0xf bank_mask:0xf
	v_add_f32_dpp v80, v80, v80 row_mirror row_mask:0xf bank_mask:0xf
	v_add_f32_dpp v81, v81, v81 row_mirror row_mask:0xf bank_mask:0xf
	v_add_f32_dpp v82, v82, v82 row_mirror row_mask:0xf bank_mask:0xf
	v_add_f32_dpp v83, v83, v83 row_mirror row_mask:0xf bank_mask:0xf
	ds_swizzle_b32 v84, v68 offset:0x401f
	ds_swizzle_b32 v85, v69 offset:0x401f
	ds_swizzle_b32 v86, v70 offset:0x401f
	ds_swizzle_b32 v87, v71 offset:0x401f
	ds_swizzle_b32 v88, v72 offset:0x401f
	ds_swizzle_b32 v89, v73 offset:0x401f
	ds_swizzle_b32 v90, v74 offset:0x401f
	ds_swizzle_b32 v91, v75 offset:0x401f
	ds_swizzle_b32 v92, v76 offset:0x401f
	ds_swizzle_b32 v93, v77 offset:0x401f
	ds_swizzle_b32 v94, v78 offset:0x401f
	ds_swizzle_b32 v95, v79 offset:0x401f
	ds_swizzle_b32 v96, v80 offset:0x401f
	ds_swizzle_b32 v97, v81 offset:0x401f
	ds_swizzle_b32 v98, v82 offset:0x401f
	ds_swizzle_b32 v99, v83 offset:0x401f
	s_waitcnt lgkmcnt(0)
	v_pk_add_f32 v[68:69], v[68:69], v[84:85]
	v_pk_add_f32 v[70:71], v[70:71], v[86:87]
	v_pk_add_f32 v[72:73], v[72:73], v[88:89]
	v_pk_add_f32 v[74:75], v[74:75], v[90:91]
	v_pk_add_f32 v[76:77], v[76:77], v[92:93]
	v_pk_add_f32 v[78:79], v[78:79], v[94:95]
	v_pk_add_f32 v[80:81], v[80:81], v[96:97]
	v_pk_add_f32 v[82:83], v[82:83], v[98:99]
	v_fmamk_f32 v68, v68, 0x3c000000, v219
	v_fmamk_f32 v69, v69, 0x3c000000, v219
	v_fmamk_f32 v70, v70, 0x3c000000, v219
	v_fmamk_f32 v71, v71, 0x3c000000, v219
	v_fmamk_f32 v72, v72, 0x3c000000, v219
	v_fmamk_f32 v73, v73, 0x3c000000, v219
	v_fmamk_f32 v74, v74, 0x3c000000, v219
	v_fmamk_f32 v75, v75, 0x3c000000, v219
	v_fmamk_f32 v76, v76, 0x3c000000, v219
	v_fmamk_f32 v77, v77, 0x3c000000, v219
	v_fmamk_f32 v78, v78, 0x3c000000, v219
	v_fmamk_f32 v79, v79, 0x3c000000, v219
	v_fmamk_f32 v80, v80, 0x3c000000, v219
	v_fmamk_f32 v81, v81, 0x3c000000, v219
	v_fmamk_f32 v82, v82, 0x3c000000, v219
	v_fmamk_f32 v83, v83, 0x3c000000, v219
	v_rsq_f32_e32 v68, v68
	v_rsq_f32_e32 v69, v69
	v_rsq_f32_e32 v70, v70
	v_rsq_f32_e32 v71, v71
	v_rsq_f32_e32 v72, v72
	v_rsq_f32_e32 v73, v73
	v_rsq_f32_e32 v74, v74
	v_rsq_f32_e32 v75, v75
	v_rsq_f32_e32 v76, v76
	v_rsq_f32_e32 v77, v77
	v_rsq_f32_e32 v78, v78
	v_rsq_f32_e32 v79, v79
	v_rsq_f32_e32 v80, v80
	v_rsq_f32_e32 v81, v81
	v_rsq_f32_e32 v82, v82
	v_rsq_f32_e32 v83, v83
	v_pk_mul_f32 v[48:49], v[48:49], v[68:69]
	v_pk_mul_f32 v[50:51], v[50:51], v[70:71]
	v_pk_mul_f32 v[52:53], v[52:53], v[72:73]
	v_pk_mul_f32 v[54:55], v[54:55], v[74:75]
	v_pk_mul_f32 v[56:57], v[56:57], v[76:77]
	v_pk_mul_f32 v[58:59], v[58:59], v[78:79]
	v_pk_mul_f32 v[60:61], v[60:61], v[80:81]
	v_pk_mul_f32 v[62:63], v[62:63], v[82:83]
	v_pk_mul_f32 v[32:33], v[32:33], v[68:69]
	v_pk_mul_f32 v[34:35], v[34:35], v[70:71]
	v_pk_mul_f32 v[36:37], v[36:37], v[72:73]
	v_pk_mul_f32 v[38:39], v[38:39], v[74:75]
	v_pk_mul_f32 v[40:41], v[40:41], v[76:77]
	v_pk_mul_f32 v[42:43], v[42:43], v[78:79]
	v_pk_mul_f32 v[44:45], v[44:45], v[80:81]
	v_pk_mul_f32 v[46:47], v[46:47], v[82:83]
	v_pk_mul_f32 v[16:17], v[16:17], v[68:69]
	v_pk_mul_f32 v[18:19], v[18:19], v[70:71]
	v_pk_mul_f32 v[20:21], v[20:21], v[72:73]
	v_pk_mul_f32 v[22:23], v[22:23], v[74:75]
	v_pk_mul_f32 v[24:25], v[24:25], v[76:77]
	v_pk_mul_f32 v[26:27], v[26:27], v[78:79]
	v_pk_mul_f32 v[28:29], v[28:29], v[80:81]
	v_pk_mul_f32 v[30:31], v[30:31], v[82:83]
	v_pk_mul_f32 v[0:1], v[0:1], v[68:69]
	v_pk_mul_f32 v[2:3], v[2:3], v[70:71]
	v_pk_mul_f32 v[4:5], v[4:5], v[72:73]
	v_pk_mul_f32 v[6:7], v[6:7], v[74:75]
	v_pk_mul_f32 v[8:9], v[8:9], v[76:77]
	v_pk_mul_f32 v[10:11], v[10:11], v[78:79]
	v_pk_mul_f32 v[12:13], v[12:13], v[80:81]
	v_pk_mul_f32 v[14:15], v[14:15], v[82:83]
	v_pk_mul_f32 v[48:49], v[48:49], v[154:155] op_sel_hi:[1,0]
	v_pk_mul_f32 v[50:51], v[50:51], v[154:155] op_sel_hi:[1,0]
	v_pk_mul_f32 v[52:53], v[52:53], v[154:155] op_sel_hi:[1,0]
	v_pk_mul_f32 v[54:55], v[54:55], v[154:155] op_sel_hi:[1,0]
	v_pk_mul_f32 v[56:57], v[56:57], v[154:155] op_sel_hi:[1,0]
	v_pk_mul_f32 v[58:59], v[58:59], v[154:155] op_sel_hi:[1,0]
	v_pk_mul_f32 v[60:61], v[60:61], v[154:155] op_sel_hi:[1,0]
	v_pk_mul_f32 v[62:63], v[62:63], v[154:155] op_sel_hi:[1,0]
	v_pk_mul_f32 v[32:33], v[32:33], v[156:157] op_sel_hi:[1,0]
	v_pk_mul_f32 v[34:35], v[34:35], v[156:157] op_sel_hi:[1,0]
	v_pk_mul_f32 v[36:37], v[36:37], v[156:157] op_sel_hi:[1,0]
	v_pk_mul_f32 v[38:39], v[38:39], v[156:157] op_sel_hi:[1,0]
	v_pk_mul_f32 v[40:41], v[40:41], v[156:157] op_sel_hi:[1,0]
	v_pk_mul_f32 v[42:43], v[42:43], v[156:157] op_sel_hi:[1,0]
	v_pk_mul_f32 v[44:45], v[44:45], v[156:157] op_sel_hi:[1,0]
	v_pk_mul_f32 v[46:47], v[46:47], v[156:157] op_sel_hi:[1,0]
	v_pk_mul_f32 v[16:17], v[16:17], v[158:159] op_sel_hi:[1,0]
	v_pk_mul_f32 v[18:19], v[18:19], v[158:159] op_sel_hi:[1,0]
	v_pk_mul_f32 v[20:21], v[20:21], v[158:159] op_sel_hi:[1,0]
	v_pk_mul_f32 v[22:23], v[22:23], v[158:159] op_sel_hi:[1,0]
	v_pk_mul_f32 v[24:25], v[24:25], v[158:159] op_sel_hi:[1,0]
	v_pk_mul_f32 v[26:27], v[26:27], v[158:159] op_sel_hi:[1,0]
	v_pk_mul_f32 v[28:29], v[28:29], v[158:159] op_sel_hi:[1,0]
	v_pk_mul_f32 v[30:31], v[30:31], v[158:159] op_sel_hi:[1,0]
	v_pk_mul_f32 v[0:1], v[0:1], v[178:179] op_sel_hi:[1,0]
	v_pk_mul_f32 v[2:3], v[2:3], v[178:179] op_sel_hi:[1,0]
	v_pk_mul_f32 v[4:5], v[4:5], v[178:179] op_sel_hi:[1,0]
	v_pk_mul_f32 v[6:7], v[6:7], v[178:179] op_sel_hi:[1,0]
	v_pk_mul_f32 v[8:9], v[8:9], v[178:179] op_sel_hi:[1,0]
	v_pk_mul_f32 v[10:11], v[10:11], v[178:179] op_sel_hi:[1,0]
	v_pk_mul_f32 v[12:13], v[12:13], v[178:179] op_sel_hi:[1,0]
	v_pk_mul_f32 v[14:15], v[14:15], v[178:179] op_sel_hi:[1,0]
	v_cvt_pk_bf16_f32 v48, v48, v48
	v_cvt_pk_bf16_f32 v49, v49, v49
	v_cvt_pk_bf16_f32 v50, v50, v50
	v_cvt_pk_bf16_f32 v51, v51, v51
	v_cvt_pk_bf16_f32 v52, v52, v52
	v_cvt_pk_bf16_f32 v53, v53, v53
	v_cvt_pk_bf16_f32 v54, v54, v54
	v_cvt_pk_bf16_f32 v55, v55, v55
	v_cvt_pk_bf16_f32 v56, v56, v56
	v_cvt_pk_bf16_f32 v57, v57, v57
	v_cvt_pk_bf16_f32 v58, v58, v58
	v_cvt_pk_bf16_f32 v59, v59, v59
	v_cvt_pk_bf16_f32 v60, v60, v60
	v_cvt_pk_bf16_f32 v61, v61, v61
	v_cvt_pk_bf16_f32 v62, v62, v62
	v_cvt_pk_bf16_f32 v63, v63, v63
	v_cvt_pk_bf16_f32 v32, v32, v32
	v_cvt_pk_bf16_f32 v33, v33, v33
	v_cvt_pk_bf16_f32 v34, v34, v34
	v_cvt_pk_bf16_f32 v35, v35, v35
	v_cvt_pk_bf16_f32 v36, v36, v36
	v_cvt_pk_bf16_f32 v37, v37, v37
	v_cvt_pk_bf16_f32 v38, v38, v38
	v_cvt_pk_bf16_f32 v39, v39, v39
	v_cvt_pk_bf16_f32 v40, v40, v40
	v_cvt_pk_bf16_f32 v41, v41, v41
	v_cvt_pk_bf16_f32 v42, v42, v42
	v_cvt_pk_bf16_f32 v43, v43, v43
	v_cvt_pk_bf16_f32 v44, v44, v44
	v_cvt_pk_bf16_f32 v45, v45, v45
	v_cvt_pk_bf16_f32 v46, v46, v46
	v_cvt_pk_bf16_f32 v47, v47, v47
	v_cvt_pk_bf16_f32 v16, v16, v16
	v_cvt_pk_bf16_f32 v17, v17, v17
	v_cvt_pk_bf16_f32 v18, v18, v18
	v_cvt_pk_bf16_f32 v19, v19, v19
	v_cvt_pk_bf16_f32 v20, v20, v20
	v_cvt_pk_bf16_f32 v21, v21, v21
	v_cvt_pk_bf16_f32 v22, v22, v22
	v_cvt_pk_bf16_f32 v23, v23, v23
	v_cvt_pk_bf16_f32 v24, v24, v24
	v_cvt_pk_bf16_f32 v25, v25, v25
	v_cvt_pk_bf16_f32 v26, v26, v26
	v_cvt_pk_bf16_f32 v27, v27, v27
	v_cvt_pk_bf16_f32 v28, v28, v28
	v_cvt_pk_bf16_f32 v29, v29, v29
	v_cvt_pk_bf16_f32 v30, v30, v30
	v_cvt_pk_bf16_f32 v31, v31, v31
	v_cvt_pk_bf16_f32 v0, v0, v0
	v_cvt_pk_bf16_f32 v1, v1, v1
	v_cvt_pk_bf16_f32 v2, v2, v2
	v_cvt_pk_bf16_f32 v3, v3, v3
	v_cvt_pk_bf16_f32 v4, v4, v4
	v_cvt_pk_bf16_f32 v5, v5, v5
	v_cvt_pk_bf16_f32 v6, v6, v6
	v_cvt_pk_bf16_f32 v7, v7, v7
	v_cvt_pk_bf16_f32 v8, v8, v8
	v_cvt_pk_bf16_f32 v9, v9, v9
	v_cvt_pk_bf16_f32 v10, v10, v10
	v_cvt_pk_bf16_f32 v11, v11, v11
	v_cvt_pk_bf16_f32 v12, v12, v12
	v_cvt_pk_bf16_f32 v13, v13, v13
	v_cvt_pk_bf16_f32 v14, v14, v14
	v_cvt_pk_bf16_f32 v15, v15, v15
	global_store_short v[176:177], v48, off
	global_store_short v[176:177], v32, off offset:64
	global_store_short v[176:177], v16, off offset:128
	global_store_short v[176:177], v0, off offset:192
	global_store_short v[176:177], v49, off offset:2048
	global_store_short v[176:177], v33, off offset:2112
	global_store_short v[176:177], v17, off offset:2176
	global_store_short v[176:177], v1, off offset:2240
	s_mov_b64 s[0:1], 0x1000
	v_lshl_add_u64 v[182:183], v[176:177], 0, s[0:1]
	global_store_short v[182:183], v50, off
	global_store_short v[182:183], v34, off offset:64
	global_store_short v[182:183], v18, off offset:128
	global_store_short v[182:183], v2, off offset:192
	global_store_short v[182:183], v51, off offset:2048
	global_store_short v[182:183], v35, off offset:2112
	global_store_short v[182:183], v19, off offset:2176
	global_store_short v[182:183], v3, off offset:2240
	s_mov_b64 s[0:1], 0x4000
	v_lshl_add_u64 v[180:181], v[176:177], 0, s[0:1]
	global_store_short v[180:181], v52, off
	global_store_short v[180:181], v36, off offset:64
	global_store_short v[180:181], v20, off offset:128
	global_store_short v[180:181], v4, off offset:192
	global_store_short v[180:181], v53, off offset:2048
	global_store_short v[180:181], v37, off offset:2112
	global_store_short v[180:181], v21, off offset:2176
	global_store_short v[180:181], v5, off offset:2240
	s_mov_b64 s[0:1], 0x5000
	v_lshl_add_u64 v[182:183], v[176:177], 0, s[0:1]
	global_store_short v[182:183], v54, off
	global_store_short v[182:183], v38, off offset:64
	global_store_short v[182:183], v22, off offset:128
	global_store_short v[182:183], v6, off offset:192
	global_store_short v[182:183], v55, off offset:2048
	global_store_short v[182:183], v39, off offset:2112
	global_store_short v[182:183], v23, off offset:2176
	global_store_short v[182:183], v7, off offset:2240
	s_mov_b64 s[0:1], 0x8000
	v_lshl_add_u64 v[180:181], v[176:177], 0, s[0:1]
	global_store_short v[180:181], v56, off
	global_store_short v[180:181], v40, off offset:64
	global_store_short v[180:181], v24, off offset:128
	global_store_short v[180:181], v8, off offset:192
	global_store_short v[180:181], v57, off offset:2048
	global_store_short v[180:181], v41, off offset:2112
	global_store_short v[180:181], v25, off offset:2176
	global_store_short v[180:181], v9, off offset:2240
	s_mov_b64 s[0:1], 0x9000
	v_lshl_add_u64 v[182:183], v[176:177], 0, s[0:1]
	global_store_short v[182:183], v58, off
	global_store_short v[182:183], v42, off offset:64
	global_store_short v[182:183], v26, off offset:128
	global_store_short v[182:183], v10, off offset:192
	global_store_short v[182:183], v59, off offset:2048
	global_store_short v[182:183], v43, off offset:2112
	global_store_short v[182:183], v27, off offset:2176
	global_store_short v[182:183], v11, off offset:2240
	s_mov_b64 s[0:1], 0xc000
	v_lshl_add_u64 v[180:181], v[176:177], 0, s[0:1]
	global_store_short v[180:181], v60, off
	global_store_short v[180:181], v44, off offset:64
	global_store_short v[180:181], v28, off offset:128
	global_store_short v[180:181], v12, off offset:192
	global_store_short v[180:181], v61, off offset:2048
	global_store_short v[180:181], v45, off offset:2112
	global_store_short v[180:181], v29, off offset:2176
	global_store_short v[180:181], v13, off offset:2240
	s_mov_b64 s[0:1], 0xd000
	v_lshl_add_u64 v[182:183], v[176:177], 0, s[0:1]
	global_store_short v[182:183], v62, off
	global_store_short v[182:183], v46, off offset:64
	global_store_short v[182:183], v30, off offset:128
	global_store_short v[182:183], v14, off offset:192
	global_store_short v[182:183], v63, off offset:2048
	global_store_short v[182:183], v47, off offset:2112
	global_store_short v[182:183], v31, off offset:2176
	s_mov_b64 s[0:1], 0xd800
	v_mov_b32_e32 v2, v15
	v_lshl_add_u64 v[0:1], v[176:177], 0, s[0:1]
	s_branch .LBB0_129

.LBB0_171:
	s_mul_i32 s0, s35, 0x6000
	v_add_u32_e32 v80, s0, v161
	v_add_u32_e32 v156, v80, v162
	ds_read_b128 v[170:173], v156 offset:0
	ds_read_b128 v[174:177], v156 offset:0x3000
	v_add_u32_e32 v169, v80, v163
	ds_read_b128 v[178:181], v169 offset:0
	ds_read_b128 v[190:193], v169 offset:0x3000
	s_waitcnt lgkmcnt(2)
	v_xor_b32_e32 v64, 0x80000000, v167
	v_mov_b32_e32 v65, v64
	v_mov_b32_e32 v66, v64
	v_mov_b32_e32 v67, v64
	v_mov_b32_e32 v68, v64
	v_mov_b32_e32 v69, v64
	v_mov_b32_e32 v70, v64
	v_mov_b32_e32 v71, v64
	v_mov_b32_e32 v72, v64
	v_mov_b32_e32 v73, v64
	v_mov_b32_e32 v74, v64
	v_mov_b32_e32 v75, v64
	v_mov_b32_e32 v76, v64
	v_mov_b32_e32 v77, v64
	v_mov_b32_e32 v78, v64
	v_mov_b32_e32 v79, v64
	v_add_u32_e32 v182, v80, v164
	v_add_u32_e32 v183, v80, v165
	v_mfma_f32_32x32x16_bf16 v[80:95], v[170:173], v[96:99], v[64:79]
	ds_read_b128 v[170:173], v182 offset:0
	v_mfma_f32_32x32x16_bf16 v[64:79], v[174:177], v[96:99], v[64:79]
	ds_read_b128 v[174:177], v182 offset:0x3000
	s_waitcnt lgkmcnt(2)
	v_mfma_f32_32x32x16_bf16 v[80:95], v[178:181], v[100:103], v[80:95]
	ds_read_b128 v[178:181], v183 offset:0
	v_mfma_f32_32x32x16_bf16 v[64:79], v[190:193], v[100:103], v[64:79]
	ds_read_b128 v[190:193], v183 offset:0x3000
	s_waitcnt lgkmcnt(2)
	v_mfma_f32_32x32x16_bf16 v[80:95], v[170:173], v[104:107], v[80:95]
	ds_read_b128 v[170:173], v156 offset:0x80
	v_mfma_f32_32x32x16_bf16 v[64:79], v[174:177], v[104:107], v[64:79]
	ds_read_b128 v[174:177], v156 offset:0x3080
	s_waitcnt lgkmcnt(2)
	v_mfma_f32_32x32x16_bf16 v[80:95], v[178:181], v[108:111], v[80:95]
	ds_read_b128 v[178:181], v169 offset:0x80
	v_mfma_f32_32x32x16_bf16 v[64:79], v[190:193], v[108:111], v[64:79]
	ds_read_b128 v[190:193], v169 offset:0x3080
	s_waitcnt lgkmcnt(2)
	v_mfma_f32_32x32x16_bf16 v[80:95], v[170:173], v[112:115], v[80:95]
	ds_read_b128 v[170:173], v182 offset:0x80
	v_mfma_f32_32x32x16_bf16 v[64:79], v[174:177], v[112:115], v[64:79]
	ds_read_b128 v[174:177], v182 offset:0x3080
	s_waitcnt lgkmcnt(2)
	v_mfma_f32_32x32x16_bf16 v[80:95], v[178:181], v[116:119], v[80:95]
	ds_read_b128 v[178:181], v183 offset:0x80
	v_mfma_f32_32x32x16_bf16 v[64:79], v[190:193], v[116:119], v[64:79]
	ds_read_b128 v[190:193], v183 offset:0x3080
	s_waitcnt lgkmcnt(2)
	v_mfma_f32_32x32x16_bf16 v[80:95], v[170:173], v[120:123], v[80:95]
	ds_read_b128 v[170:173], v156 offset:0x100
	v_mfma_f32_32x32x16_bf16 v[64:79], v[174:177], v[120:123], v[64:79]
	ds_read_b128 v[174:177], v156 offset:0x3100
	s_waitcnt lgkmcnt(2)
	v_mfma_f32_32x32x16_bf16 v[80:95], v[178:181], v[124:127], v[80:95]
	ds_read_b128 v[178:181], v169 offset:0x100
	v_mfma_f32_32x32x16_bf16 v[64:79], v[190:193], v[124:127], v[64:79]
	ds_read_b128 v[190:193], v169 offset:0x3100
	s_waitcnt lgkmcnt(2)
	v_mfma_f32_32x32x16_bf16 v[80:95], v[170:173], v[128:131], v[80:95]
	ds_read_b128 v[170:173], v182 offset:0x100
	v_mfma_f32_32x32x16_bf16 v[64:79], v[174:177], v[128:131], v[64:79]
	ds_read_b128 v[174:177], v182 offset:0x3100
	s_waitcnt lgkmcnt(2)
	v_mfma_f32_32x32x16_bf16 v[80:95], v[178:181], v[132:135], v[80:95]
	ds_read_b128 v[178:181], v183 offset:0x100
	v_mfma_f32_32x32x16_bf16 v[64:79], v[190:193], v[132:135], v[64:79]
	ds_read_b128 v[190:193], v183 offset:0x3100
	s_waitcnt lgkmcnt(2)
	v_mfma_f32_32x32x16_bf16 v[80:95], v[170:173], v[136:139], v[80:95]
	s_waitcnt lgkmcnt(0)
	v_mfma_f32_32x32x16_bf16 v[64:79], v[174:177], v[136:139], v[64:79]
	v_mfma_f32_32x32x16_bf16 v[80:95], v[178:181], v[140:143], v[80:95]
	s_cmp_eq_u32 s31, 0
	s_cselect_b64 s[2:3], -1, 0
	s_cmp_lg_u32 s31, 0
	v_mfma_f32_32x32x16_bf16 v[64:79], v[190:193], v[140:143], v[64:79]
	s_nop 7
	v_max_f32_e32 v156, v80, v81
	v_max3_f32 v156, v156, v82, v83
	v_max3_f32 v156, v156, v84, v85
	v_max3_f32 v156, v156, v86, v87
	v_max3_f32 v156, v156, v88, v89
	v_max3_f32 v156, v156, v90, v91
	v_max3_f32 v156, v156, v92, v93
	v_max3_f32 v156, v156, v94, v95
	v_max3_f32 v156, v156, v64, v65
	v_max3_f32 v156, v156, v66, v67
	v_max3_f32 v156, v156, v68, v69
	v_max3_f32 v156, v156, v70, v71
	v_max3_f32 v156, v156, v72, v73
	v_max3_f32 v156, v156, v74, v75
	v_max3_f32 v156, v156, v76, v77
	v_max3_f32 v156, v156, v78, v79
	s_cbranch_scc0 .Lmx3_first
	v_cmp_ge_f32_e32 vcc, s62, v156
	s_cmp_lg_u64 vcc, exec
	s_mov_b64 s[24:25], 0
	s_mov_b64 s[22:23], 0
	s_cbranch_scc1 .Lmx3_slow
	v_mov_b32_e32 v169, 1.0
	s_branch .LBB0_183
.Lmx3_first:
	v_mov_b32_e32 v169, v156
	s_nop 1
	v_permlane32_swap_b32_e32 v156, v169
	v_max_f32_e32 v169, v156, v169
	s_branch .LBB0_176

.LBB0_183:
	v_exp_f32_e32 v80, v80
	v_exp_f32_e32 v81, v81
	v_exp_f32_e32 v82, v82
	v_exp_f32_e32 v83, v83
	v_exp_f32_e32 v84, v84
	v_exp_f32_e32 v156, v64
	v_exp_f32_e32 v85, v85
	v_add_f32_e32 v64, v81, v80
	v_exp_f32_e32 v86, v86
	v_add_f32_e32 v64, v82, v64
	v_exp_f32_e32 v87, v87
	v_add_f32_e32 v64, v83, v64
	v_exp_f32_e32 v88, v88
	v_add_f32_e32 v64, v84, v64
	v_exp_f32_e32 v89, v89
	v_add_f32_e32 v64, v85, v64
	v_exp_f32_e32 v90, v90
	v_add_f32_e32 v64, v86, v64
	v_exp_f32_e32 v91, v91
	v_add_f32_e32 v64, v87, v64
	v_exp_f32_e32 v92, v92
	v_add_f32_e32 v64, v88, v64
	v_exp_f32_e32 v93, v93
	v_add_f32_e32 v64, v89, v64
	v_exp_f32_e32 v94, v94
	v_add_f32_e32 v64, v90, v64
	v_exp_f32_e32 v95, v95
	v_add_f32_e32 v64, v91, v64
	v_add_f32_e32 v64, v92, v64
	v_exp_f32_e32 v65, v65
	v_add_f32_e32 v64, v93, v64
	v_exp_f32_e32 v170, v66
	v_add_f32_e32 v64, v94, v64
	v_exp_f32_e32 v171, v67
	v_add_f32_e32 v64, v95, v64
	v_exp_f32_e32 v172, v68
	v_add_f32_e32 v64, v156, v64
	v_exp_f32_e32 v173, v69
	v_add_f32_e32 v64, v65, v64
	v_exp_f32_e32 v174, v70
	v_add_f32_e32 v64, v170, v64
	v_exp_f32_e32 v175, v71
	v_add_f32_e32 v64, v171, v64
	v_exp_f32_e32 v176, v72
	v_add_f32_e32 v64, v172, v64
	v_exp_f32_e32 v177, v73
	v_add_f32_e32 v64, v173, v64
	v_exp_f32_e32 v178, v74
	v_add_f32_e32 v64, v174, v64
	v_exp_f32_e32 v179, v75
	v_add_f32_e32 v64, v175, v64
	v_exp_f32_e32 v180, v76
	v_add_f32_e32 v64, v176, v64
	v_exp_f32_e32 v181, v77
	v_add_f32_e32 v64, v177, v64
	v_exp_f32_e32 v182, v78
	v_add_f32_e32 v64, v178, v64
	v_exp_f32_e32 v183, v79
	v_add_f32_e32 v64, v179, v64
	v_add_f32_e32 v64, v180, v64
	v_add_f32_e32 v64, v181, v64
	v_add_f32_e32 v64, v182, v64
	v_add_f32_e32 v64, v183, v64
	s_add_i32 s31, s31, 1
	v_fmac_f32_e32 v64, v168, v169
	v_cvt_pk_bf16_f32 v66, v80, v81
	v_cvt_pk_bf16_f32 v67, v82, v83
	v_cvt_pk_bf16_f32 v68, v84, v85
	v_cvt_pk_bf16_f32 v69, v86, v87
	v_cvt_pk_bf16_f32 v70, v88, v89
	v_cvt_pk_bf16_f32 v71, v90, v91
	v_cvt_pk_bf16_f32 v72, v92, v93
	v_cvt_pk_bf16_f32 v73, v94, v95
	v_cvt_pk_bf16_f32 v74, v156, v65
	v_cvt_pk_bf16_f32 v75, v170, v171
	v_cvt_pk_bf16_f32 v76, v172, v173
	v_cvt_pk_bf16_f32 v77, v174, v175
	v_cvt_pk_bf16_f32 v78, v176, v177
	v_cvt_pk_bf16_f32 v79, v178, v179
	v_cvt_pk_bf16_f32 v80, v180, v181
	v_cvt_pk_bf16_f32 v81, v182, v183
	s_nop 0
	v_permlane32_swap_b32_e32 v66, v68
	v_permlane32_swap_b32_e32 v67, v69
	v_permlane32_swap_b32_e32 v70, v72
	v_permlane32_swap_b32_e32 v71, v73
	v_permlane32_swap_b32_e32 v74, v76
	v_permlane32_swap_b32_e32 v75, v77
	v_permlane32_swap_b32_e32 v78, v80
	v_permlane32_swap_b32_e32 v79, v81
	v_lshl_add_u32 v65, s35, 14, v166
	ds_read_b64_tr_b16 v[82:83], v65 offset:0
	ds_read_b64_tr_b16 v[84:85], v65 offset:0x800
	ds_read_b64_tr_b16 v[86:87], v65 offset:0x1000
	ds_read_b64_tr_b16 v[88:89], v65 offset:0x1800
	ds_read_b64_tr_b16 v[90:91], v65 offset:0x2000
	ds_read_b64_tr_b16 v[92:93], v65 offset:0x2800
	ds_read_b64_tr_b16 v[168:169], v65 offset:0x3000
	ds_read_b64_tr_b16 v[170:171], v65 offset:0x3800
	ds_read_b64_tr_b16 v[172:173], v65 offset:0x200
	ds_read_b64_tr_b16 v[174:175], v65 offset:0xa00
	ds_read_b64_tr_b16 v[176:177], v65 offset:0x1200
	ds_read_b64_tr_b16 v[178:179], v65 offset:0x1a00
	ds_read_b64_tr_b16 v[180:181], v65 offset:0x2200
	ds_read_b64_tr_b16 v[182:183], v65 offset:0x2a00
	ds_read_b64_tr_b16 v[190:191], v65 offset:0x3200
	ds_read_b64_tr_b16 v[192:193], v65 offset:0x3a00
	s_waitcnt lgkmcnt(8)
	s_nop 0
	v_mfma_f32_32x32x16_bf16 v[48:63], v[66:69], v[82:85], v[48:63]
	ds_read_b64_tr_b16 v[82:83], v65 offset:0x400
	ds_read_b64_tr_b16 v[84:85], v65 offset:0xc00
	v_mfma_f32_32x32x16_bf16 v[48:63], v[70:73], v[86:89], v[48:63]
	ds_read_b64_tr_b16 v[86:87], v65 offset:0x1400
	ds_read_b64_tr_b16 v[88:89], v65 offset:0x1c00
	v_mfma_f32_32x32x16_bf16 v[48:63], v[74:77], v[90:93], v[48:63]
	ds_read_b64_tr_b16 v[90:91], v65 offset:0x2400
	ds_read_b64_tr_b16 v[92:93], v65 offset:0x2c00
	v_mfma_f32_32x32x16_bf16 v[48:63], v[78:81], v[168:171], v[48:63]
	ds_read_b64_tr_b16 v[168:169], v65 offset:0x3400
	ds_read_b64_tr_b16 v[170:171], v65 offset:0x3c00
	s_waitcnt lgkmcnt(8)
	v_mfma_f32_32x32x16_bf16 v[32:47], v[66:69], v[172:175], v[32:47]
	ds_read_b64_tr_b16 v[172:173], v65 offset:0x600
	ds_read_b64_tr_b16 v[174:175], v65 offset:0xe00
	v_mfma_f32_32x32x16_bf16 v[32:47], v[70:73], v[176:179], v[32:47]
	ds_read_b64_tr_b16 v[176:177], v65 offset:0x1600
	ds_read_b64_tr_b16 v[178:179], v65 offset:0x1e00
	v_mfma_f32_32x32x16_bf16 v[32:47], v[74:77], v[180:183], v[32:47]
	ds_read_b64_tr_b16 v[180:181], v65 offset:0x2600
	ds_read_b64_tr_b16 v[182:183], v65 offset:0x2e00
	v_mfma_f32_32x32x16_bf16 v[32:47], v[78:81], v[190:193], v[32:47]
	ds_read_b64_tr_b16 v[190:191], v65 offset:0x3600
	ds_read_b64_tr_b16 v[192:193], v65 offset:0x3e00
	s_waitcnt lgkmcnt(8)
	v_mfma_f32_32x32x16_bf16 v[16:31], v[66:69], v[82:85], v[16:31]
	s_waitcnt lgkmcnt(0)
	v_mfma_f32_32x32x16_bf16 v[16:31], v[70:73], v[86:89], v[16:31]
	v_mfma_f32_32x32x16_bf16 v[16:31], v[74:77], v[90:93], v[16:31]
	v_mfma_f32_32x32x16_bf16 v[16:31], v[78:81], v[168:171], v[16:31]
	v_mfma_f32_32x32x16_bf16 v[0:15], v[66:69], v[172:175], v[0:15]
	s_waitcnt vmcnt(0)
	s_add_i32 s34, s34, 64
	s_cmp_eq_u32 s31, 32
	s_waitcnt vmcnt(0) lgkmcnt(0)
	s_barrier
	v_mfma_f32_32x32x16_bf16 v[0:15], v[70:73], v[176:179], v[0:15]
	v_mfma_f32_32x32x16_bf16 v[0:15], v[74:77], v[180:183], v[0:15]
	v_mfma_f32_32x32x16_bf16 v[0:15], v[78:81], v[190:193], v[0:15]
	s_cbranch_scc1 .LBB0_185
	v_mov_b32_e32 v168, v64
	s_and_b32 s35, s31, 1
	s_cmp_eq_u32 s31, 31
	s_cbranch_scc0 .LBB0_170
	s_branch .LBB0_171
.LBB0_185:
	v_mov_b32_e32 v66, v64
	s_nop 1
	v_permlane32_swap_b32_e32 v64, v66
	v_add_f32_e32 v64, v64, v66
	s_and_saveexec_b64 s[0:1], s[6:7]
	s_cbranch_execz .LBB0_128
	ds_write_b32 v160, v64
	s_branch .LBB0_128
